# quads start P4 staggered (quad index x s_sleep 5) so their epilogues stop hitting HBM in the same instant
# baseline (speedup 1.0000x reference)
; #define PG8_STAGE(bufoff, gbase, voff) do { _Pragma("unroll") for (int _i = 0; _i < 2; ++_i) \
;         __builtin_amdgcn_global_load_lds((const unsigned*)((const char*)(gbase) + (voff)[_i]), (PG8_LAS unsigned*)(lds + (bufoff) + ldsw + _i * 8192), 16, 0, 0); } while (0)
; #define PG8_WAIT_V(n) asm volatile("s_waitcnt vmcnt(" #n ")" ::: "memory")
; #define PG8_BAR __builtin_amdgcn_s_barrier()
; template <class Epi, class Sched, bool ALIGN_EPI = false, bool SP2 = false>
; __device__ __forceinline__ void gemm_phase(PG8_LAS unsigned char* lds, const Gemm g, const Sched& S, const Epi& E, volatile PG8_LAS unsigned* sw = nullptr) {
;     ...
;     const char* cA = (const char*)g.A + (size_t)cur.pm * tstep; const char* cB = (const char*)g.Bt + (size_t)cur.pn * tstep;
;     S.a_ready(cur);
;     if constexpr (SP2) {
;         PG8_STAGE(PG8_SB(0, 0), cB, voffB); PG8_STAGE(PG8_SB(0, 1), cB + hstep, voffB); PG8_STAGE(PG8_SA(0, 0), cA, voffA); PG8_STAGE(PG8_SA(0, 1), cA + hstep, voffA);
;         if (wr == 1) PG8_BAR;
;         PG8_WAIT_V(2); PG8_BAR;
;         PG8_STAGE(PG8_SB(1, 0), cB + kstep, voffB); PG8_STAGE(PG8_SA(1, 0), cA + kstep, voffA); PG8_STAGE(PG8_SB(1, 1), cB + hstep + kstep, voffB);
;         PG8_WAIT_V(6); PG8_BAR;
;     } else {
;         PG8_STAGE(PG8_SB(0, 0), cB, voffB); PG8_STAGE(PG8_SA(0, 0), cA, voffA); PG8_STAGE(PG8_SB(0, 1), cB + hstep, voffB); PG8_STAGE(PG8_SA(0, 1), cA + hstep, voffA);
;         if (wr == 1) PG8_BAR;
;         PG8_WAIT_V(4); PG8_BAR;
; __global__ void __launch_bounds__(NWAVES * 64, 2) fwd(Args a) {
;     ...
;         pg8::Gemm g{CATg, WoT, GROWS, D, D}; GroupOrder S; S.init(D, gk, xh, cph);
;         EpiOut E{a.in[I_XP], a.in[I_XS], X1g, XG2g, rss2, g1t, G2t, asc, pm0};
;         pg8::gemm_phase<EpiOut, GroupOrder, PG8_ALIGN, PG8_SP2>(lds + RING_OFF, g, S, E, SW_PTR(4));
.LBB0_435:
	s_or_b64 exec, exec, s[0:1]
	s_add_u32 s20, s62, 0x98000
	v_readlane_b32 s0, v250, 10
	s_addc_u32 s21, s63, 0
	s_lshl_b32 s70, s0, 5
	s_add_u32 s71, s16, 0x4000000
	s_addc_u32 s72, s17, 0
	s_cmp_lt_i32 s97, 64
	s_cselect_b64 s[18:19], -1, 0
	s_ashr_i32 s0, s97, 31
	s_lshr_b32 s0, s0, 27
	s_add_i32 s0, s97, s0
	s_ashr_i32 s1, s0, 5
	s_andn2_b32 s0, s0, 31
	s_sub_i32 s0, s97, s0
	s_lshl_b32 s1, s1, 3
	s_add_i32 s1, s1, s77
	s_and_b32 s4, s0, 7
	s_or_b32 s12, s1, s4
	v_mov_b32_e32 v2, v0
	v_readlane_b32 s92, v250, 50
	s_waitcnt lgkmcnt(0)
	s_barrier
	s_and_b32 s4, s101, 7
	s_lshl_b32 s4, s4, 3
	s_bfe_u32 s5, s101, 0x30003
	s_or_b32 s4, s4, s5
.Lstag_loop:
	s_cmp_eq_u32 s4, 0
	s_cbranch_scc1 .Lstag_done
	s_sleep 5
	s_sub_u32 s4, s4, 1
	s_branch .Lstag_loop
.Lstag_done:
	s_ashr_i32 s10, s0, 3
	s_ashr_i32 s13, s12, 31
	s_and_b64 vcc, exec, s[18:19]
	v_readfirstlane_b32 s4, v2
	v_readlane_b32 s93, v250, 51
	s_cbranch_vccz .LBB0_457
	v_lshlrev_b32_e32 v1, 4, v2
	v_add_u32_e32 v4, 0x2000, v1
	v_ashrrev_i32_e32 v3, 31, v4
	v_lshrrev_b32_e32 v3, 22, v3
	v_add_u32_e32 v3, v4, v3
	v_ashrrev_i32_e32 v3, 10, v3
	v_mul_i32_i24_e32 v5, 0x400, v3
	v_sub_u32_e32 v4, v4, v5
	v_lshrrev_b32_e32 v5, 4, v4
	v_bitop3_b32 v5, v5, v4, 32 bitop3:0x6c
	v_ashrrev_i32_e32 v4, 31, v5
	v_lshrrev_b32_e32 v4, 26, v4
	s_ashr_i32 s11, s10, 31
	v_add_u32_e32 v6, v5, v4
	v_lshlrev_b32_e32 v7, 3, v3
	s_lshl_b64 s[0:1], s[12:13], 19
	s_lshl_b64 s[6:7], s[10:11], 19
	v_ashrrev_i32_e32 v4, 6, v6
	v_and_b32_e32 v7, -16, v7
	s_add_u32 s48, s84, s6
	v_add_u32_e32 v7, v4, v7
	s_addc_u32 s49, s85, s7
	v_and_b32_e32 v8, 3, v4
	s_mov_b32 s7, 0x1ffffe0
	v_lshrrev_b32_e32 v9, 2, v7
	v_lshlrev_b32_e32 v10, 1, v7
	v_and_or_b32 v8, v7, s7, v8
	v_and_b32_e32 v9, 4, v9
	v_and_b32_e32 v10, 24, v10
	v_and_b32_e32 v6, 0xc0, v6
	v_or3_b32 v8, v8, v9, v10
	v_sub_u32_e32 v5, v5, v6
	v_mov_b32_e32 v10, 1
	v_lshlrev_b32_e32 v9, 5, v3
	v_ashrrev_i16_sdwa v5, v10, sext(v5) dst_sel:DWORD dst_unused:UNUSED_PAD src0_sel:DWORD src1_sel:BYTE_0
	v_and_b32_e32 v9, 32, v9
	v_bfe_i32 v5, v5, 0, 16
	v_add_lshl_u32 v6, v9, v5, 1
	v_lshl_add_u32 v146, v8, 7, v6
	v_lshl_add_u32 v148, v7, 7, v6
	v_bfe_i32 v6, v2, 27, 1
	v_lshrrev_b32_e32 v6, 22, v6
	v_add_u32_e32 v6, v1, v6
	v_and_b32_e32 v6, 0xfffffc00, v6
	v_sub_u32_e32 v1, v1, v6
	v_lshrrev_b32_e32 v6, 4, v1
	v_ashrrev_i32_e32 v7, 31, v2
	v_bitop3_b32 v1, v6, v1, 32 bitop3:0x6c
	v_lshrrev_b32_e32 v7, 26, v7
	v_ashrrev_i32_e32 v6, 31, v1
	v_add_u32_e32 v7, v2, v7
	v_lshrrev_b32_e32 v6, 26, v6
	v_ashrrev_i32_e32 v7, 6, v7
	v_add_u32_e32 v8, v1, v6
	v_lshlrev_b32_e32 v9, 3, v7
	s_add_u32 s46, s2, s0
	v_ashrrev_i32_e32 v6, 6, v8
	v_and_b32_e32 v9, -16, v9
	s_addc_u32 s47, s3, s1
	s_ashr_i32 s6, s4, 6
	v_add_u32_e32 v9, v6, v9
	s_ashr_i32 s5, s4, 8
	s_lshl_b32 s11, s6, 10
	v_and_b32_e32 v11, 3, v6
	v_lshrrev_b32_e32 v12, 2, v9
	v_lshlrev_b32_e32 v13, 1, v9
	v_and_b32_e32 v8, 0xc0, v8
	s_add_u32 s0, s46, 0x4000
	v_and_or_b32 v11, v9, s7, v11
	v_and_b32_e32 v12, 4, v12
	v_and_b32_e32 v13, 24, v13
	v_sub_u32_e32 v1, v1, v8
	s_addc_u32 s1, s47, 0
	v_or3_b32 v11, v11, v12, v13
	v_lshlrev_b32_e32 v12, 5, v7
	v_ashrrev_i16_sdwa v1, v10, sext(v1) dst_sel:DWORD dst_unused:UNUSED_PAD src0_sel:DWORD src1_sel:BYTE_0
	s_add_u32 s8, s48, 0x4000
	v_and_b32_e32 v12, 32, v12
	v_bfe_i32 v8, v1, 0, 16
	s_addc_u32 s9, s49, 0
	v_add_lshl_u32 v1, v12, v8, 1
	s_add_i32 s13, s11, 0
	v_lshl_add_u32 v150, v11, 7, v1
	s_add_i32 m0, s13, 0x10000
	v_lshl_add_u32 v152, v9, 7, v1
	global_load_lds_dwordx4 v150, s[48:49]
	s_add_i32 m0, s13, 0x12000
	s_add_i32 s14, s13, 0x2000
	global_load_lds_dwordx4 v146, s[48:49]
	s_add_i32 m0, s13, 0x14000
	s_add_i32 s15, s13, 0x4000
	global_load_lds_dwordx4 v150, s[8:9]
	s_add_i32 m0, s13, 0x16000
	s_add_i32 s33, s13, 0x6000
	global_load_lds_dwordx4 v146, s[8:9]
	s_mov_b32 m0, s13
	v_mov_b32_e32 v155, 0
	global_load_lds_dwordx4 v152, s[46:47]
	s_mov_b32 m0, s14
	s_cmp_eq_u32 s5, 1
	global_load_lds_dwordx4 v148, s[46:47]
	s_mov_b32 m0, s15
	s_mov_b32 s40, 0x10000
	global_load_lds_dwordx4 v152, s[0:1]
	s_mov_b32 m0, s33
	v_mov_b32_e32 v151, v155
	global_load_lds_dwordx4 v148, s[0:1]
	v_mov_b32_e32 v147, v155
	v_mov_b32_e32 v153, v155
	s_cselect_b64 s[0:1], -1, 0
	s_cmp_lg_u32 s5, 1
	v_mov_b32_e32 v149, v155
	s_cbranch_scc1 .LBB0_438
	s_barrier
